# prep_ew: conv input rows touched ahead of the tap loop
# baseline (speedup 1.0000x reference)
; DI float bflo(unsigned u) { return __uint_as_float(u << 16); }
; DI float bfhi(unsigned u) { return __uint_as_float(u & 0xffff0000u); }
; DI void prep_ew_item(const Params& p, int l, int item, bf16_t* lds) {
;     ...
;     const int tl = t;
; #pragma unroll
;     for (int part = 0; part < 3; ++part) {
;       const int ch = part * 512 + lane * 8;
;       float a[8];
; #pragma unroll
;       for (int j = 0; j < 8; ++j) a[j] = 0.f;
; #pragma unroll
;       for (int i = 0; i < 4; ++i) {
;         const int ts = tl - 3 + i;
;         if (ts >= 0) {
;           u32x4 v = *(const u32x4*)(RC + (size_t)ts * 1536 + ch); unsigned w[4] = {v.x, v.y, v.z, v.w};
;           const float* cw = p.convw + ((size_t)l * 4 + i) * 1536 + ch;
;           f32x4 c0 = *(const f32x4*)cw, c1 = *(const f32x4*)(cw + 4);
;           a[0] += bflo(w[0]) * c0[0]; a[1] += bfhi(w[0]) * c0[1]; a[2] += bflo(w[1]) * c0[2]; a[3] += bfhi(w[1]) * c0[3];
;           a[4] += bflo(w[2]) * c1[0]; a[5] += bfhi(w[2]) * c1[1]; a[6] += bflo(w[3]) * c1[2]; a[7] += bfhi(w[3]) * c1[3];
;         }
.LBB0_848:
	v_add_u32_e32 v56, s4, v0
	v_add_u32_e32 v40, 0xffffb800, v56
	v_mov_b32_e32 v50, 0
	v_add_u32_e32 v57, 0xffffb7fd, v56
	v_cmp_lt_i32_e64 s[42:43], 2, v40
	v_mov_b32_e32 v51, 0
	s_waitcnt vmcnt(1)
	v_max_i32_e32 v77, 0, v57
	v_mad_u64_u32 v[78:79], s[98:99], v77, s57, v[6:7]
	global_load_dword v76, v[78:79], off
	global_load_dword v76, v[78:79], off offset:1024
	global_load_dword v76, v[78:79], off offset:2048
	v_add_u32_e32 v77, 1, v57
	v_max_i32_e32 v77, 0, v77
	v_mad_u64_u32 v[78:79], s[98:99], v77, s57, v[6:7]
	global_load_dword v76, v[78:79], off
	global_load_dword v76, v[78:79], off offset:1024
	global_load_dword v76, v[78:79], off offset:2048
	v_add_u32_e32 v77, 2, v57
	v_max_i32_e32 v77, 0, v77
	v_mad_u64_u32 v[78:79], s[98:99], v77, s57, v[6:7]
	global_load_dword v76, v[78:79], off
	global_load_dword v76, v[78:79], off offset:1024
	global_load_dword v76, v[78:79], off offset:2048
	v_add_u32_e32 v77, 3, v57
	v_max_i32_e32 v77, 0, v77
	v_mad_u64_u32 v[78:79], s[98:99], v77, s57, v[6:7]
	global_load_dword v76, v[78:79], off
	global_load_dword v76, v[78:79], off offset:1024
	global_load_dword v76, v[78:79], off offset:2048
	v_add_u32_e32 v77, 4, v57
	v_max_i32_e32 v77, 0, v77
	v_mad_u64_u32 v[78:79], s[98:99], v77, s57, v[6:7]
	global_load_dword v76, v[78:79], off
	global_load_dword v76, v[78:79], off offset:1024
	global_load_dword v76, v[78:79], off offset:2048
	v_mov_b32_e32 v42, 0
	v_mov_b32_e32 v43, 0
	v_mov_b32_e32 v44, 0
	v_mov_b32_e32 v45, v50
	v_mov_b32_e32 v46, v50
	v_mov_b32_e32 v47, v50
	v_mov_b32_e32 v48, 0
	v_mov_b32_e32 v49, 0
	s_and_saveexec_b64 s[26:27], s[42:43]
	s_cbranch_execz .LBB0_850
	v_mad_u64_u32 v[42:43], s[6:7], v57, s57, v[6:7]
	global_load_dwordx4 v[46:49], v[42:43], off
	global_load_dwordx4 v[50:53], v[8:9], off offset:16
	s_nop 0
	global_load_dwordx4 v[42:45], v[8:9], off
	s_waitcnt vmcnt(2)
	v_lshlrev_b32_e32 v54, 16, v46
	v_and_b32_e32 v55, 0xffff0000, v46
	v_lshlrev_b32_e32 v46, 16, v47
	v_and_b32_e32 v47, 0xffff0000, v47
	s_waitcnt vmcnt(0)
	v_pk_fma_f32 v[44:45], v[44:45], v[46:47], 0 op_sel_hi:[1,1,0]
	v_lshlrev_b32_e32 v46, 16, v48
	v_and_b32_e32 v47, 0xffff0000, v48
	v_lshlrev_b32_e32 v48, 16, v49
	v_and_b32_e32 v49, 0xffff0000, v49
	v_pk_fma_f32 v[46:47], v[50:51], v[46:47], 0 op_sel_hi:[1,1,0]
	v_pk_fma_f32 v[50:51], v[52:53], v[48:49], 0 op_sel_hi:[1,1,0]
	v_pk_fma_f32 v[42:43], v[42:43], v[54:55], 0 op_sel_hi:[1,1,0]
	v_mov_b32_e32 v48, v50
	v_mov_b32_e32 v49, v51
